# attention waits + lag DMA + scan block v6 (tree-form dot chain, VALU-only DPP gaps)
# baseline (speedup 1.0000x reference)
.LBB0_1010:
	s_mov_b64 s[78:79], -1
	s_and_b64 vcc, exec, s[70:71]
	s_cbranch_vccz .LBB0_1014
	s_setprio 1
	s_and_b32 s55, s53, 1
	s_lshl_b32 s56, s55, 14
	s_mul_i32 s55, s55, 0xaa00
	v_or_b32_e32 v99, s56, v143
	v_lshl_add_u32 v96, v106, 2, s55
	v_lshl_add_u32 v97, v101, 2, s55
	v_mov_b32_e32 v98, s55
	v_add_u32_e32 v99, 0x15400, v99
	s_waitcnt vmcnt(0)
	ds_read_b128 v[170:173], v96 offset:256
	ds_read_b128 v[174:177], v96 offset:512
	ds_read_b128 v[166:169], v96
	ds_read_b128 v[182:185], v96 offset:1024
	ds_read_b128 v[178:181], v96 offset:768
	ds_read_b32 v186, v97 offset:1280
	ds_read_b64 v[188:189], v98 offset:1344
	ds_read_b128 v[194:197], v96 offset:1616
	ds_read_b128 v[198:201], v96 offset:1872
	ds_read_b128 v[190:193], v96 offset:1360
	ds_read_b128 v[206:209], v96 offset:2384
	ds_read_b128 v[202:205], v96 offset:2128
	ds_read_b32 v210, v97 offset:2640
	ds_read_b64 v[220:221], v98 offset:2704
	v_mov_b64_e32 v[48:49], v[92:93]
	v_mov_b64_e32 v[52:53], v[94:95]
	s_waitcnt lgkmcnt(7)
	v_pk_mul_f32 v[58:59], v[52:53], v[170:171] op_sel_hi:[0,1]
	v_pk_mul_f32 v[102:103], v[48:49], v[174:175] op_sel_hi:[0,1]
	ds_read_b128 v[32:35], v96 offset:2976
	v_pk_fma_f32 v[58:59], v[52:53], v[172:173], v[58:59] op_sel:[1,0,0]
	v_pk_fma_f32 v[102:103], v[48:49], v[176:177], v[102:103] op_sel:[1,0,0]
	ds_read_b128 v[36:39], v96 offset:3232
	ds_read_b128 v[28:31], v96 offset:2720
	v_pk_add_f32 v[58:59], v[58:59], v[102:103]
	v_pk_mul_f32 v[64:65], v[186:187], v[182:183] op_sel_hi:[0,1]
	v_pk_mul_f32 v[66:67], v[186:187], v[184:185] op_sel_hi:[0,1]
	v_add_f32_dpp v58, v58, v58 row_ror:8 row_mask:0xf bank_mask:0xf bound_ctrl:1
	v_pk_fma_f32 v[64:65], v[52:53], v[166:167], v[64:65]
	v_pk_fma_f32 v[66:67], v[48:49], v[168:169], v[66:67]
	v_add_f32_dpp v58, v58, v58 row_ror:4 row_mask:0xf bank_mask:0xf bound_ctrl:1
	v_add_f32_dpp v60, v59, v59 row_ror:8 row_mask:0xf bank_mask:0xf bound_ctrl:1
	ds_read_b128 v[44:47], v96 offset:3744
	v_add_f32_dpp v58, v58, v58 row_ror:2 row_mask:0xf bank_mask:0xf bound_ctrl:1
	v_fma_f32 v61, v186, v189, v60
	ds_read_b128 v[40:43], v96 offset:3488
	v_add_f32_dpp v58, v58, v58 row_ror:1 row_mask:0xf bank_mask:0xf bound_ctrl:1
	v_pk_fma_f32 v[52:53], v[58:59], v[178:179], v[64:65] op_sel_hi:[0,1,1]
	v_pk_fma_f32 v[48:49], v[58:59], v[180:181], v[66:67] op_sel_hi:[0,1,1]
	v_fma_f32 v61, v58, v188, v61
	ds_read_b32 v54, v97 offset:4000
	ds_read_b64 v[56:57], v98 offset:4064
	ds_write_b32 v99, v61
	s_waitcnt lgkmcnt(8)
	v_pk_mul_f32 v[58:59], v[52:53], v[194:195] op_sel_hi:[0,1]
	v_pk_mul_f32 v[102:103], v[48:49], v[198:199] op_sel_hi:[0,1]
	ds_read_b128 v[170:173], v96 offset:4336
	v_pk_fma_f32 v[58:59], v[52:53], v[196:197], v[58:59] op_sel:[1,0,0]
	v_pk_fma_f32 v[102:103], v[48:49], v[200:201], v[102:103] op_sel:[1,0,0]
	ds_read_b128 v[174:177], v96 offset:4592
	ds_read_b128 v[166:169], v96 offset:4080
	v_pk_add_f32 v[58:59], v[58:59], v[102:103]
	v_pk_mul_f32 v[64:65], v[210:211], v[206:207] op_sel_hi:[0,1]
	v_pk_mul_f32 v[66:67], v[210:211], v[208:209] op_sel_hi:[0,1]
	v_add_f32_dpp v58, v58, v58 row_ror:8 row_mask:0xf bank_mask:0xf bound_ctrl:1
	v_pk_fma_f32 v[64:65], v[52:53], v[190:191], v[64:65]
	v_pk_fma_f32 v[66:67], v[48:49], v[192:193], v[66:67]
	v_add_f32_dpp v58, v58, v58 row_ror:4 row_mask:0xf bank_mask:0xf bound_ctrl:1
	v_add_f32_dpp v60, v59, v59 row_ror:8 row_mask:0xf bank_mask:0xf bound_ctrl:1
	ds_read_b128 v[182:185], v96 offset:5104
	v_add_f32_dpp v58, v58, v58 row_ror:2 row_mask:0xf bank_mask:0xf bound_ctrl:1
	v_fma_f32 v61, v210, v221, v60
	ds_read_b128 v[178:181], v96 offset:4848
	v_add_f32_dpp v58, v58, v58 row_ror:1 row_mask:0xf bank_mask:0xf bound_ctrl:1
	v_pk_fma_f32 v[52:53], v[58:59], v[202:203], v[64:65] op_sel_hi:[0,1,1]
	v_pk_fma_f32 v[48:49], v[58:59], v[204:205], v[66:67] op_sel_hi:[0,1,1]
	v_fma_f32 v61, v58, v220, v61
	ds_read_b32 v186, v97 offset:5360
	ds_read_b64 v[188:189], v98 offset:5424
	ds_write_b32 v99, v61 offset:512
	s_waitcnt lgkmcnt(9)
	v_pk_mul_f32 v[58:59], v[52:53], v[32:33] op_sel_hi:[0,1]
	v_pk_mul_f32 v[102:103], v[48:49], v[36:37] op_sel_hi:[0,1]
	ds_read_b128 v[194:197], v96 offset:5696
	v_pk_fma_f32 v[58:59], v[52:53], v[34:35], v[58:59] op_sel:[1,0,0]
	v_pk_fma_f32 v[102:103], v[48:49], v[38:39], v[102:103] op_sel:[1,0,0]
	ds_read_b128 v[198:201], v96 offset:5952
	ds_read_b128 v[190:193], v96 offset:5440
	v_pk_add_f32 v[58:59], v[58:59], v[102:103]
	v_pk_mul_f32 v[64:65], v[54:55], v[44:45] op_sel_hi:[0,1]
	v_pk_mul_f32 v[66:67], v[54:55], v[46:47] op_sel_hi:[0,1]
	v_add_f32_dpp v58, v58, v58 row_ror:8 row_mask:0xf bank_mask:0xf bound_ctrl:1
	v_pk_fma_f32 v[64:65], v[52:53], v[28:29], v[64:65]
	v_pk_fma_f32 v[66:67], v[48:49], v[30:31], v[66:67]
	v_add_f32_dpp v58, v58, v58 row_ror:4 row_mask:0xf bank_mask:0xf bound_ctrl:1
	v_add_f32_dpp v60, v59, v59 row_ror:8 row_mask:0xf bank_mask:0xf bound_ctrl:1
	ds_read_b128 v[206:209], v96 offset:6464
	v_add_f32_dpp v58, v58, v58 row_ror:2 row_mask:0xf bank_mask:0xf bound_ctrl:1
	v_fma_f32 v61, v54, v57, v60
	ds_read_b128 v[202:205], v96 offset:6208
	v_add_f32_dpp v58, v58, v58 row_ror:1 row_mask:0xf bank_mask:0xf bound_ctrl:1
	v_pk_fma_f32 v[52:53], v[58:59], v[40:41], v[64:65] op_sel_hi:[0,1,1]
	v_pk_fma_f32 v[48:49], v[58:59], v[42:43], v[66:67] op_sel_hi:[0,1,1]
	v_fma_f32 v61, v58, v56, v61
	ds_read_b32 v210, v97 offset:6720
	ds_read_b64 v[220:221], v98 offset:6784
	ds_write_b32 v99, v61 offset:1024
	s_waitcnt lgkmcnt(9)
	v_pk_mul_f32 v[58:59], v[52:53], v[170:171] op_sel_hi:[0,1]
	v_pk_mul_f32 v[102:103], v[48:49], v[174:175] op_sel_hi:[0,1]
	ds_read_b128 v[32:35], v96 offset:7056
	v_pk_fma_f32 v[58:59], v[52:53], v[172:173], v[58:59] op_sel:[1,0,0]
	v_pk_fma_f32 v[102:103], v[48:49], v[176:177], v[102:103] op_sel:[1,0,0]
	ds_read_b128 v[36:39], v96 offset:7312
	ds_read_b128 v[28:31], v96 offset:6800
	v_pk_add_f32 v[58:59], v[58:59], v[102:103]
	v_pk_mul_f32 v[64:65], v[186:187], v[182:183] op_sel_hi:[0,1]
	v_pk_mul_f32 v[66:67], v[186:187], v[184:185] op_sel_hi:[0,1]
	v_add_f32_dpp v58, v58, v58 row_ror:8 row_mask:0xf bank_mask:0xf bound_ctrl:1
	v_pk_fma_f32 v[64:65], v[52:53], v[166:167], v[64:65]
	v_pk_fma_f32 v[66:67], v[48:49], v[168:169], v[66:67]
	v_add_f32_dpp v58, v58, v58 row_ror:4 row_mask:0xf bank_mask:0xf bound_ctrl:1
	v_add_f32_dpp v60, v59, v59 row_ror:8 row_mask:0xf bank_mask:0xf bound_ctrl:1
	ds_read_b128 v[44:47], v96 offset:7824
	v_add_f32_dpp v58, v58, v58 row_ror:2 row_mask:0xf bank_mask:0xf bound_ctrl:1
	v_fma_f32 v61, v186, v189, v60
	ds_read_b128 v[40:43], v96 offset:7568
	v_add_f32_dpp v58, v58, v58 row_ror:1 row_mask:0xf bank_mask:0xf bound_ctrl:1
	v_pk_fma_f32 v[52:53], v[58:59], v[178:179], v[64:65] op_sel_hi:[0,1,1]
	v_pk_fma_f32 v[48:49], v[58:59], v[180:181], v[66:67] op_sel_hi:[0,1,1]
	v_fma_f32 v61, v58, v188, v61
	ds_read_b32 v54, v97 offset:8080
	ds_read_b64 v[56:57], v98 offset:8144
	ds_write_b32 v99, v61 offset:1536
	s_waitcnt lgkmcnt(9)
	v_pk_mul_f32 v[58:59], v[52:53], v[194:195] op_sel_hi:[0,1]
	v_pk_mul_f32 v[102:103], v[48:49], v[198:199] op_sel_hi:[0,1]
	ds_read_b128 v[170:173], v96 offset:8416
	v_pk_fma_f32 v[58:59], v[52:53], v[196:197], v[58:59] op_sel:[1,0,0]
	v_pk_fma_f32 v[102:103], v[48:49], v[200:201], v[102:103] op_sel:[1,0,0]
	ds_read_b128 v[174:177], v96 offset:8672
	ds_read_b128 v[166:169], v96 offset:8160
	v_pk_add_f32 v[58:59], v[58:59], v[102:103]
	v_pk_mul_f32 v[64:65], v[210:211], v[206:207] op_sel_hi:[0,1]
	v_pk_mul_f32 v[66:67], v[210:211], v[208:209] op_sel_hi:[0,1]
	v_add_f32_dpp v58, v58, v58 row_ror:8 row_mask:0xf bank_mask:0xf bound_ctrl:1
	v_pk_fma_f32 v[64:65], v[52:53], v[190:191], v[64:65]
	v_pk_fma_f32 v[66:67], v[48:49], v[192:193], v[66:67]
	v_add_f32_dpp v58, v58, v58 row_ror:4 row_mask:0xf bank_mask:0xf bound_ctrl:1
	v_add_f32_dpp v60, v59, v59 row_ror:8 row_mask:0xf bank_mask:0xf bound_ctrl:1
	ds_read_b128 v[182:185], v96 offset:9184
	v_add_f32_dpp v58, v58, v58 row_ror:2 row_mask:0xf bank_mask:0xf bound_ctrl:1
	v_fma_f32 v61, v210, v221, v60
	ds_read_b128 v[178:181], v96 offset:8928
	v_add_f32_dpp v58, v58, v58 row_ror:1 row_mask:0xf bank_mask:0xf bound_ctrl:1
	v_pk_fma_f32 v[52:53], v[58:59], v[202:203], v[64:65] op_sel_hi:[0,1,1]
	v_pk_fma_f32 v[48:49], v[58:59], v[204:205], v[66:67] op_sel_hi:[0,1,1]
	v_fma_f32 v61, v58, v220, v61
	ds_read_b32 v186, v97 offset:9440
	ds_read_b64 v[188:189], v98 offset:9504
	ds_write_b32 v99, v61 offset:2048
	s_waitcnt lgkmcnt(9)
	v_pk_mul_f32 v[58:59], v[52:53], v[32:33] op_sel_hi:[0,1]
	v_pk_mul_f32 v[102:103], v[48:49], v[36:37] op_sel_hi:[0,1]
	ds_read_b128 v[194:197], v96 offset:9776
	v_pk_fma_f32 v[58:59], v[52:53], v[34:35], v[58:59] op_sel:[1,0,0]
	v_pk_fma_f32 v[102:103], v[48:49], v[38:39], v[102:103] op_sel:[1,0,0]
	ds_read_b128 v[198:201], v96 offset:10032
	ds_read_b128 v[190:193], v96 offset:9520
	v_pk_add_f32 v[58:59], v[58:59], v[102:103]
	v_pk_mul_f32 v[64:65], v[54:55], v[44:45] op_sel_hi:[0,1]
	v_pk_mul_f32 v[66:67], v[54:55], v[46:47] op_sel_hi:[0,1]
	v_add_f32_dpp v58, v58, v58 row_ror:8 row_mask:0xf bank_mask:0xf bound_ctrl:1
	v_pk_fma_f32 v[64:65], v[52:53], v[28:29], v[64:65]
	v_pk_fma_f32 v[66:67], v[48:49], v[30:31], v[66:67]
	v_add_f32_dpp v58, v58, v58 row_ror:4 row_mask:0xf bank_mask:0xf bound_ctrl:1
	v_add_f32_dpp v60, v59, v59 row_ror:8 row_mask:0xf bank_mask:0xf bound_ctrl:1
	ds_read_b128 v[206:209], v96 offset:10544
	v_add_f32_dpp v58, v58, v58 row_ror:2 row_mask:0xf bank_mask:0xf bound_ctrl:1
	v_fma_f32 v61, v54, v57, v60
	ds_read_b128 v[202:205], v96 offset:10288
	v_add_f32_dpp v58, v58, v58 row_ror:1 row_mask:0xf bank_mask:0xf bound_ctrl:1
	v_pk_fma_f32 v[52:53], v[58:59], v[40:41], v[64:65] op_sel_hi:[0,1,1]
	v_pk_fma_f32 v[48:49], v[58:59], v[42:43], v[66:67] op_sel_hi:[0,1,1]
	v_fma_f32 v61, v58, v56, v61
	ds_read_b32 v210, v97 offset:10800
	ds_read_b64 v[220:221], v98 offset:10864
	ds_write_b32 v99, v61 offset:2560
	s_waitcnt lgkmcnt(9)
	v_pk_mul_f32 v[58:59], v[52:53], v[170:171] op_sel_hi:[0,1]
	v_pk_mul_f32 v[102:103], v[48:49], v[174:175] op_sel_hi:[0,1]
	ds_read_b128 v[32:35], v96 offset:11136
	v_pk_fma_f32 v[58:59], v[52:53], v[172:173], v[58:59] op_sel:[1,0,0]
	v_pk_fma_f32 v[102:103], v[48:49], v[176:177], v[102:103] op_sel:[1,0,0]
	ds_read_b128 v[36:39], v96 offset:11392
	ds_read_b128 v[28:31], v96 offset:10880
	v_pk_add_f32 v[58:59], v[58:59], v[102:103]
	v_pk_mul_f32 v[64:65], v[186:187], v[182:183] op_sel_hi:[0,1]
	v_pk_mul_f32 v[66:67], v[186:187], v[184:185] op_sel_hi:[0,1]
	v_add_f32_dpp v58, v58, v58 row_ror:8 row_mask:0xf bank_mask:0xf bound_ctrl:1
	v_pk_fma_f32 v[64:65], v[52:53], v[166:167], v[64:65]
	v_pk_fma_f32 v[66:67], v[48:49], v[168:169], v[66:67]
	v_add_f32_dpp v58, v58, v58 row_ror:4 row_mask:0xf bank_mask:0xf bound_ctrl:1
	v_add_f32_dpp v60, v59, v59 row_ror:8 row_mask:0xf bank_mask:0xf bound_ctrl:1
	ds_read_b128 v[44:47], v96 offset:11904
	v_add_f32_dpp v58, v58, v58 row_ror:2 row_mask:0xf bank_mask:0xf bound_ctrl:1
	v_fma_f32 v61, v186, v189, v60
	ds_read_b128 v[40:43], v96 offset:11648
	v_add_f32_dpp v58, v58, v58 row_ror:1 row_mask:0xf bank_mask:0xf bound_ctrl:1
	v_pk_fma_f32 v[52:53], v[58:59], v[178:179], v[64:65] op_sel_hi:[0,1,1]
	v_pk_fma_f32 v[48:49], v[58:59], v[180:181], v[66:67] op_sel_hi:[0,1,1]
	v_fma_f32 v61, v58, v188, v61
	ds_read_b32 v54, v97 offset:12160
	ds_read_b64 v[56:57], v98 offset:12224
	ds_write_b32 v99, v61 offset:3072
	s_waitcnt lgkmcnt(9)
	v_pk_mul_f32 v[58:59], v[52:53], v[194:195] op_sel_hi:[0,1]
	v_pk_mul_f32 v[102:103], v[48:49], v[198:199] op_sel_hi:[0,1]
	ds_read_b128 v[170:173], v96 offset:12496
	v_pk_fma_f32 v[58:59], v[52:53], v[196:197], v[58:59] op_sel:[1,0,0]
	v_pk_fma_f32 v[102:103], v[48:49], v[200:201], v[102:103] op_sel:[1,0,0]
	ds_read_b128 v[174:177], v96 offset:12752
	ds_read_b128 v[166:169], v96 offset:12240
	v_pk_add_f32 v[58:59], v[58:59], v[102:103]
	v_pk_mul_f32 v[64:65], v[210:211], v[206:207] op_sel_hi:[0,1]
	v_pk_mul_f32 v[66:67], v[210:211], v[208:209] op_sel_hi:[0,1]
	v_add_f32_dpp v58, v58, v58 row_ror:8 row_mask:0xf bank_mask:0xf bound_ctrl:1
	v_pk_fma_f32 v[64:65], v[52:53], v[190:191], v[64:65]
	v_pk_fma_f32 v[66:67], v[48:49], v[192:193], v[66:67]
	v_add_f32_dpp v58, v58, v58 row_ror:4 row_mask:0xf bank_mask:0xf bound_ctrl:1
	v_add_f32_dpp v60, v59, v59 row_ror:8 row_mask:0xf bank_mask:0xf bound_ctrl:1
	ds_read_b128 v[182:185], v96 offset:13264
	v_add_f32_dpp v58, v58, v58 row_ror:2 row_mask:0xf bank_mask:0xf bound_ctrl:1
	v_fma_f32 v61, v210, v221, v60
	ds_read_b128 v[178:181], v96 offset:13008
	v_add_f32_dpp v58, v58, v58 row_ror:1 row_mask:0xf bank_mask:0xf bound_ctrl:1
	v_pk_fma_f32 v[52:53], v[58:59], v[202:203], v[64:65] op_sel_hi:[0,1,1]
	v_pk_fma_f32 v[48:49], v[58:59], v[204:205], v[66:67] op_sel_hi:[0,1,1]
	v_fma_f32 v61, v58, v220, v61
	ds_read_b32 v186, v97 offset:13520
	ds_read_b64 v[188:189], v98 offset:13584
	ds_write_b32 v99, v61 offset:3584
	s_waitcnt lgkmcnt(9)
	v_pk_mul_f32 v[58:59], v[52:53], v[32:33] op_sel_hi:[0,1]
	v_pk_mul_f32 v[102:103], v[48:49], v[36:37] op_sel_hi:[0,1]
	ds_read_b128 v[194:197], v96 offset:13856
	v_pk_fma_f32 v[58:59], v[52:53], v[34:35], v[58:59] op_sel:[1,0,0]
	v_pk_fma_f32 v[102:103], v[48:49], v[38:39], v[102:103] op_sel:[1,0,0]
	ds_read_b128 v[198:201], v96 offset:14112
	ds_read_b128 v[190:193], v96 offset:13600
	v_pk_add_f32 v[58:59], v[58:59], v[102:103]
	v_pk_mul_f32 v[64:65], v[54:55], v[44:45] op_sel_hi:[0,1]
	v_pk_mul_f32 v[66:67], v[54:55], v[46:47] op_sel_hi:[0,1]
	v_add_f32_dpp v58, v58, v58 row_ror:8 row_mask:0xf bank_mask:0xf bound_ctrl:1
	v_pk_fma_f32 v[64:65], v[52:53], v[28:29], v[64:65]
	v_pk_fma_f32 v[66:67], v[48:49], v[30:31], v[66:67]
	v_add_f32_dpp v58, v58, v58 row_ror:4 row_mask:0xf bank_mask:0xf bound_ctrl:1
	v_add_f32_dpp v60, v59, v59 row_ror:8 row_mask:0xf bank_mask:0xf bound_ctrl:1
	ds_read_b128 v[206:209], v96 offset:14624
	v_add_f32_dpp v58, v58, v58 row_ror:2 row_mask:0xf bank_mask:0xf bound_ctrl:1
	v_fma_f32 v61, v54, v57, v60
	ds_read_b128 v[202:205], v96 offset:14368
	v_add_f32_dpp v58, v58, v58 row_ror:1 row_mask:0xf bank_mask:0xf bound_ctrl:1
	v_pk_fma_f32 v[52:53], v[58:59], v[40:41], v[64:65] op_sel_hi:[0,1,1]
	v_pk_fma_f32 v[48:49], v[58:59], v[42:43], v[66:67] op_sel_hi:[0,1,1]
	v_fma_f32 v61, v58, v56, v61
	ds_read_b32 v210, v97 offset:14880
	ds_read_b64 v[220:221], v98 offset:14944
	ds_write_b32 v99, v61 offset:4096
	s_waitcnt lgkmcnt(9)
	v_pk_mul_f32 v[58:59], v[52:53], v[170:171] op_sel_hi:[0,1]
	v_pk_mul_f32 v[102:103], v[48:49], v[174:175] op_sel_hi:[0,1]
	ds_read_b128 v[32:35], v96 offset:15216
	v_pk_fma_f32 v[58:59], v[52:53], v[172:173], v[58:59] op_sel:[1,0,0]
	v_pk_fma_f32 v[102:103], v[48:49], v[176:177], v[102:103] op_sel:[1,0,0]
	ds_read_b128 v[36:39], v96 offset:15472
	ds_read_b128 v[28:31], v96 offset:14960
	v_pk_add_f32 v[58:59], v[58:59], v[102:103]
	v_pk_mul_f32 v[64:65], v[186:187], v[182:183] op_sel_hi:[0,1]
	v_pk_mul_f32 v[66:67], v[186:187], v[184:185] op_sel_hi:[0,1]
	v_add_f32_dpp v58, v58, v58 row_ror:8 row_mask:0xf bank_mask:0xf bound_ctrl:1
	v_pk_fma_f32 v[64:65], v[52:53], v[166:167], v[64:65]
	v_pk_fma_f32 v[66:67], v[48:49], v[168:169], v[66:67]
	v_add_f32_dpp v58, v58, v58 row_ror:4 row_mask:0xf bank_mask:0xf bound_ctrl:1
	v_add_f32_dpp v60, v59, v59 row_ror:8 row_mask:0xf bank_mask:0xf bound_ctrl:1
	ds_read_b128 v[44:47], v96 offset:15984
	v_add_f32_dpp v58, v58, v58 row_ror:2 row_mask:0xf bank_mask:0xf bound_ctrl:1
	v_fma_f32 v61, v186, v189, v60
	ds_read_b128 v[40:43], v96 offset:15728
	v_add_f32_dpp v58, v58, v58 row_ror:1 row_mask:0xf bank_mask:0xf bound_ctrl:1
	v_pk_fma_f32 v[52:53], v[58:59], v[178:179], v[64:65] op_sel_hi:[0,1,1]
	v_pk_fma_f32 v[48:49], v[58:59], v[180:181], v[66:67] op_sel_hi:[0,1,1]
	v_fma_f32 v61, v58, v188, v61
	ds_read_b32 v54, v97 offset:16240
	ds_read_b64 v[56:57], v98 offset:16304
	ds_write_b32 v99, v61 offset:4608
	s_waitcnt lgkmcnt(9)
	v_pk_mul_f32 v[58:59], v[52:53], v[194:195] op_sel_hi:[0,1]
	v_pk_mul_f32 v[102:103], v[48:49], v[198:199] op_sel_hi:[0,1]
	ds_read_b128 v[170:173], v96 offset:16576
	v_pk_fma_f32 v[58:59], v[52:53], v[196:197], v[58:59] op_sel:[1,0,0]
	v_pk_fma_f32 v[102:103], v[48:49], v[200:201], v[102:103] op_sel:[1,0,0]
	ds_read_b128 v[174:177], v96 offset:16832
	ds_read_b128 v[166:169], v96 offset:16320
	v_pk_add_f32 v[58:59], v[58:59], v[102:103]
	v_pk_mul_f32 v[64:65], v[210:211], v[206:207] op_sel_hi:[0,1]
	v_pk_mul_f32 v[66:67], v[210:211], v[208:209] op_sel_hi:[0,1]
	v_add_f32_dpp v58, v58, v58 row_ror:8 row_mask:0xf bank_mask:0xf bound_ctrl:1
	v_pk_fma_f32 v[64:65], v[52:53], v[190:191], v[64:65]
	v_pk_fma_f32 v[66:67], v[48:49], v[192:193], v[66:67]
	v_add_f32_dpp v58, v58, v58 row_ror:4 row_mask:0xf bank_mask:0xf bound_ctrl:1
	v_add_f32_dpp v60, v59, v59 row_ror:8 row_mask:0xf bank_mask:0xf bound_ctrl:1
	ds_read_b128 v[182:185], v96 offset:17344
	v_add_f32_dpp v58, v58, v58 row_ror:2 row_mask:0xf bank_mask:0xf bound_ctrl:1
	v_fma_f32 v61, v210, v221, v60
	ds_read_b128 v[178:181], v96 offset:17088
	v_add_f32_dpp v58, v58, v58 row_ror:1 row_mask:0xf bank_mask:0xf bound_ctrl:1
	v_pk_fma_f32 v[52:53], v[58:59], v[202:203], v[64:65] op_sel_hi:[0,1,1]
	v_pk_fma_f32 v[48:49], v[58:59], v[204:205], v[66:67] op_sel_hi:[0,1,1]
	v_fma_f32 v61, v58, v220, v61
	ds_read_b32 v186, v97 offset:17600
	ds_read_b64 v[188:189], v98 offset:17664
	ds_write_b32 v99, v61 offset:5120
	s_waitcnt lgkmcnt(9)
	v_pk_mul_f32 v[58:59], v[52:53], v[32:33] op_sel_hi:[0,1]
	v_pk_mul_f32 v[102:103], v[48:49], v[36:37] op_sel_hi:[0,1]
	ds_read_b128 v[194:197], v96 offset:17936
	v_pk_fma_f32 v[58:59], v[52:53], v[34:35], v[58:59] op_sel:[1,0,0]
	v_pk_fma_f32 v[102:103], v[48:49], v[38:39], v[102:103] op_sel:[1,0,0]
	ds_read_b128 v[198:201], v96 offset:18192
	ds_read_b128 v[190:193], v96 offset:17680
	v_pk_add_f32 v[58:59], v[58:59], v[102:103]
	v_pk_mul_f32 v[64:65], v[54:55], v[44:45] op_sel_hi:[0,1]
	v_pk_mul_f32 v[66:67], v[54:55], v[46:47] op_sel_hi:[0,1]
	v_add_f32_dpp v58, v58, v58 row_ror:8 row_mask:0xf bank_mask:0xf bound_ctrl:1
	v_pk_fma_f32 v[64:65], v[52:53], v[28:29], v[64:65]
	v_pk_fma_f32 v[66:67], v[48:49], v[30:31], v[66:67]
	v_add_f32_dpp v58, v58, v58 row_ror:4 row_mask:0xf bank_mask:0xf bound_ctrl:1
	v_add_f32_dpp v60, v59, v59 row_ror:8 row_mask:0xf bank_mask:0xf bound_ctrl:1
	ds_read_b128 v[206:209], v96 offset:18704
	v_add_f32_dpp v58, v58, v58 row_ror:2 row_mask:0xf bank_mask:0xf bound_ctrl:1
	v_fma_f32 v61, v54, v57, v60
	ds_read_b128 v[202:205], v96 offset:18448
	v_add_f32_dpp v58, v58, v58 row_ror:1 row_mask:0xf bank_mask:0xf bound_ctrl:1
	v_pk_fma_f32 v[52:53], v[58:59], v[40:41], v[64:65] op_sel_hi:[0,1,1]
	v_pk_fma_f32 v[48:49], v[58:59], v[42:43], v[66:67] op_sel_hi:[0,1,1]
	v_fma_f32 v61, v58, v56, v61
	ds_read_b32 v210, v97 offset:18960
	ds_read_b64 v[220:221], v98 offset:19024
	ds_write_b32 v99, v61 offset:5632
	s_waitcnt lgkmcnt(9)
	v_pk_mul_f32 v[58:59], v[52:53], v[170:171] op_sel_hi:[0,1]
	v_pk_mul_f32 v[102:103], v[48:49], v[174:175] op_sel_hi:[0,1]
	ds_read_b128 v[32:35], v96 offset:19296
	v_pk_fma_f32 v[58:59], v[52:53], v[172:173], v[58:59] op_sel:[1,0,0]
	v_pk_fma_f32 v[102:103], v[48:49], v[176:177], v[102:103] op_sel:[1,0,0]
	ds_read_b128 v[36:39], v96 offset:19552
	ds_read_b128 v[28:31], v96 offset:19040
	v_pk_add_f32 v[58:59], v[58:59], v[102:103]
	v_pk_mul_f32 v[64:65], v[186:187], v[182:183] op_sel_hi:[0,1]
	v_pk_mul_f32 v[66:67], v[186:187], v[184:185] op_sel_hi:[0,1]
	v_add_f32_dpp v58, v58, v58 row_ror:8 row_mask:0xf bank_mask:0xf bound_ctrl:1
	v_pk_fma_f32 v[64:65], v[52:53], v[166:167], v[64:65]
	v_pk_fma_f32 v[66:67], v[48:49], v[168:169], v[66:67]
	v_add_f32_dpp v58, v58, v58 row_ror:4 row_mask:0xf bank_mask:0xf bound_ctrl:1
	v_add_f32_dpp v60, v59, v59 row_ror:8 row_mask:0xf bank_mask:0xf bound_ctrl:1
	ds_read_b128 v[44:47], v96 offset:20064
	v_add_f32_dpp v58, v58, v58 row_ror:2 row_mask:0xf bank_mask:0xf bound_ctrl:1
	v_fma_f32 v61, v186, v189, v60
	ds_read_b128 v[40:43], v96 offset:19808
	v_add_f32_dpp v58, v58, v58 row_ror:1 row_mask:0xf bank_mask:0xf bound_ctrl:1
	v_pk_fma_f32 v[52:53], v[58:59], v[178:179], v[64:65] op_sel_hi:[0,1,1]
	v_pk_fma_f32 v[48:49], v[58:59], v[180:181], v[66:67] op_sel_hi:[0,1,1]
	v_fma_f32 v61, v58, v188, v61
	ds_read_b32 v54, v97 offset:20320
	ds_read_b64 v[56:57], v98 offset:20384
	ds_write_b32 v99, v61 offset:6144
	s_waitcnt lgkmcnt(9)
	v_pk_mul_f32 v[58:59], v[52:53], v[194:195] op_sel_hi:[0,1]
	v_pk_mul_f32 v[102:103], v[48:49], v[198:199] op_sel_hi:[0,1]
	ds_read_b128 v[170:173], v96 offset:20656
	v_pk_fma_f32 v[58:59], v[52:53], v[196:197], v[58:59] op_sel:[1,0,0]
	v_pk_fma_f32 v[102:103], v[48:49], v[200:201], v[102:103] op_sel:[1,0,0]
	ds_read_b128 v[174:177], v96 offset:20912
	ds_read_b128 v[166:169], v96 offset:20400
	v_pk_add_f32 v[58:59], v[58:59], v[102:103]
	v_pk_mul_f32 v[64:65], v[210:211], v[206:207] op_sel_hi:[0,1]
	v_pk_mul_f32 v[66:67], v[210:211], v[208:209] op_sel_hi:[0,1]
	v_add_f32_dpp v58, v58, v58 row_ror:8 row_mask:0xf bank_mask:0xf bound_ctrl:1
	v_pk_fma_f32 v[64:65], v[52:53], v[190:191], v[64:65]
	v_pk_fma_f32 v[66:67], v[48:49], v[192:193], v[66:67]
	v_add_f32_dpp v58, v58, v58 row_ror:4 row_mask:0xf bank_mask:0xf bound_ctrl:1
	v_add_f32_dpp v60, v59, v59 row_ror:8 row_mask:0xf bank_mask:0xf bound_ctrl:1
	ds_read_b128 v[182:185], v96 offset:21424
	v_add_f32_dpp v58, v58, v58 row_ror:2 row_mask:0xf bank_mask:0xf bound_ctrl:1
	v_fma_f32 v61, v210, v221, v60
	ds_read_b128 v[178:181], v96 offset:21168
	v_add_f32_dpp v58, v58, v58 row_ror:1 row_mask:0xf bank_mask:0xf bound_ctrl:1
	v_pk_fma_f32 v[52:53], v[58:59], v[202:203], v[64:65] op_sel_hi:[0,1,1]
	v_pk_fma_f32 v[48:49], v[58:59], v[204:205], v[66:67] op_sel_hi:[0,1,1]
	v_fma_f32 v61, v58, v220, v61
	ds_read_b32 v186, v97 offset:21680
	ds_read_b64 v[188:189], v98 offset:21744
	ds_write_b32 v99, v61 offset:6656
	s_waitcnt lgkmcnt(9)
	v_pk_mul_f32 v[58:59], v[52:53], v[32:33] op_sel_hi:[0,1]
	v_pk_mul_f32 v[102:103], v[48:49], v[36:37] op_sel_hi:[0,1]
	ds_read_b128 v[194:197], v96 offset:22016
	v_pk_fma_f32 v[58:59], v[52:53], v[34:35], v[58:59] op_sel:[1,0,0]
	v_pk_fma_f32 v[102:103], v[48:49], v[38:39], v[102:103] op_sel:[1,0,0]
	ds_read_b128 v[198:201], v96 offset:22272
	ds_read_b128 v[190:193], v96 offset:21760
	v_pk_add_f32 v[58:59], v[58:59], v[102:103]
	v_pk_mul_f32 v[64:65], v[54:55], v[44:45] op_sel_hi:[0,1]
	v_pk_mul_f32 v[66:67], v[54:55], v[46:47] op_sel_hi:[0,1]
	v_add_f32_dpp v58, v58, v58 row_ror:8 row_mask:0xf bank_mask:0xf bound_ctrl:1
	v_pk_fma_f32 v[64:65], v[52:53], v[28:29], v[64:65]
	v_pk_fma_f32 v[66:67], v[48:49], v[30:31], v[66:67]
	v_add_f32_dpp v58, v58, v58 row_ror:4 row_mask:0xf bank_mask:0xf bound_ctrl:1
	v_add_f32_dpp v60, v59, v59 row_ror:8 row_mask:0xf bank_mask:0xf bound_ctrl:1
	ds_read_b128 v[206:209], v96 offset:22784
	v_add_f32_dpp v58, v58, v58 row_ror:2 row_mask:0xf bank_mask:0xf bound_ctrl:1
	v_fma_f32 v61, v54, v57, v60
	ds_read_b128 v[202:205], v96 offset:22528
	v_add_f32_dpp v58, v58, v58 row_ror:1 row_mask:0xf bank_mask:0xf bound_ctrl:1
	v_pk_fma_f32 v[52:53], v[58:59], v[40:41], v[64:65] op_sel_hi:[0,1,1]
	v_pk_fma_f32 v[48:49], v[58:59], v[42:43], v[66:67] op_sel_hi:[0,1,1]
	v_fma_f32 v61, v58, v56, v61
	ds_read_b32 v210, v97 offset:23040
	ds_read_b64 v[220:221], v98 offset:23104
	ds_write_b32 v99, v61 offset:7168
	s_waitcnt lgkmcnt(9)
	v_pk_mul_f32 v[58:59], v[52:53], v[170:171] op_sel_hi:[0,1]
	v_pk_mul_f32 v[102:103], v[48:49], v[174:175] op_sel_hi:[0,1]
	ds_read_b128 v[32:35], v96 offset:23376
	v_pk_fma_f32 v[58:59], v[52:53], v[172:173], v[58:59] op_sel:[1,0,0]
	v_pk_fma_f32 v[102:103], v[48:49], v[176:177], v[102:103] op_sel:[1,0,0]
	ds_read_b128 v[36:39], v96 offset:23632
	ds_read_b128 v[28:31], v96 offset:23120
	v_pk_add_f32 v[58:59], v[58:59], v[102:103]
	v_pk_mul_f32 v[64:65], v[186:187], v[182:183] op_sel_hi:[0,1]
	v_pk_mul_f32 v[66:67], v[186:187], v[184:185] op_sel_hi:[0,1]
	v_add_f32_dpp v58, v58, v58 row_ror:8 row_mask:0xf bank_mask:0xf bound_ctrl:1
	v_pk_fma_f32 v[64:65], v[52:53], v[166:167], v[64:65]
	v_pk_fma_f32 v[66:67], v[48:49], v[168:169], v[66:67]
	v_add_f32_dpp v58, v58, v58 row_ror:4 row_mask:0xf bank_mask:0xf bound_ctrl:1
	v_add_f32_dpp v60, v59, v59 row_ror:8 row_mask:0xf bank_mask:0xf bound_ctrl:1
	ds_read_b128 v[44:47], v96 offset:24144
	v_add_f32_dpp v58, v58, v58 row_ror:2 row_mask:0xf bank_mask:0xf bound_ctrl:1
	v_fma_f32 v61, v186, v189, v60
	ds_read_b128 v[40:43], v96 offset:23888
	v_add_f32_dpp v58, v58, v58 row_ror:1 row_mask:0xf bank_mask:0xf bound_ctrl:1
	v_pk_fma_f32 v[52:53], v[58:59], v[178:179], v[64:65] op_sel_hi:[0,1,1]
	v_pk_fma_f32 v[48:49], v[58:59], v[180:181], v[66:67] op_sel_hi:[0,1,1]
	v_fma_f32 v61, v58, v188, v61
	ds_read_b32 v54, v97 offset:24400
	ds_read_b64 v[56:57], v98 offset:24464
	ds_write_b32 v99, v61 offset:7680
	s_waitcnt lgkmcnt(9)
	v_pk_mul_f32 v[58:59], v[52:53], v[194:195] op_sel_hi:[0,1]
	v_pk_mul_f32 v[102:103], v[48:49], v[198:199] op_sel_hi:[0,1]
	ds_read_b128 v[170:173], v96 offset:24736
	v_pk_fma_f32 v[58:59], v[52:53], v[196:197], v[58:59] op_sel:[1,0,0]
	v_pk_fma_f32 v[102:103], v[48:49], v[200:201], v[102:103] op_sel:[1,0,0]
	ds_read_b128 v[174:177], v96 offset:24992
	ds_read_b128 v[166:169], v96 offset:24480
	v_pk_add_f32 v[58:59], v[58:59], v[102:103]
	v_pk_mul_f32 v[64:65], v[210:211], v[206:207] op_sel_hi:[0,1]
	v_pk_mul_f32 v[66:67], v[210:211], v[208:209] op_sel_hi:[0,1]
	v_add_f32_dpp v58, v58, v58 row_ror:8 row_mask:0xf bank_mask:0xf bound_ctrl:1
	v_pk_fma_f32 v[64:65], v[52:53], v[190:191], v[64:65]
	v_pk_fma_f32 v[66:67], v[48:49], v[192:193], v[66:67]
	v_add_f32_dpp v58, v58, v58 row_ror:4 row_mask:0xf bank_mask:0xf bound_ctrl:1
	v_add_f32_dpp v60, v59, v59 row_ror:8 row_mask:0xf bank_mask:0xf bound_ctrl:1
	ds_read_b128 v[182:185], v96 offset:25504
	v_add_f32_dpp v58, v58, v58 row_ror:2 row_mask:0xf bank_mask:0xf bound_ctrl:1
	v_fma_f32 v61, v210, v221, v60
	ds_read_b128 v[178:181], v96 offset:25248
	v_add_f32_dpp v58, v58, v58 row_ror:1 row_mask:0xf bank_mask:0xf bound_ctrl:1
	v_pk_fma_f32 v[52:53], v[58:59], v[202:203], v[64:65] op_sel_hi:[0,1,1]
	v_pk_fma_f32 v[48:49], v[58:59], v[204:205], v[66:67] op_sel_hi:[0,1,1]
	v_fma_f32 v61, v58, v220, v61
	ds_read_b32 v186, v97 offset:25760
	ds_read_b64 v[188:189], v98 offset:25824
	ds_write_b32 v99, v61 offset:8192
	s_waitcnt lgkmcnt(9)
	v_pk_mul_f32 v[58:59], v[52:53], v[32:33] op_sel_hi:[0,1]
	v_pk_mul_f32 v[102:103], v[48:49], v[36:37] op_sel_hi:[0,1]
	ds_read_b128 v[194:197], v96 offset:26096
	v_pk_fma_f32 v[58:59], v[52:53], v[34:35], v[58:59] op_sel:[1,0,0]
	v_pk_fma_f32 v[102:103], v[48:49], v[38:39], v[102:103] op_sel:[1,0,0]
	ds_read_b128 v[198:201], v96 offset:26352
	ds_read_b128 v[190:193], v96 offset:25840
	v_pk_add_f32 v[58:59], v[58:59], v[102:103]
	v_pk_mul_f32 v[64:65], v[54:55], v[44:45] op_sel_hi:[0,1]
	v_pk_mul_f32 v[66:67], v[54:55], v[46:47] op_sel_hi:[0,1]
	v_add_f32_dpp v58, v58, v58 row_ror:8 row_mask:0xf bank_mask:0xf bound_ctrl:1
	v_pk_fma_f32 v[64:65], v[52:53], v[28:29], v[64:65]
	v_pk_fma_f32 v[66:67], v[48:49], v[30:31], v[66:67]
	v_add_f32_dpp v58, v58, v58 row_ror:4 row_mask:0xf bank_mask:0xf bound_ctrl:1
	v_add_f32_dpp v60, v59, v59 row_ror:8 row_mask:0xf bank_mask:0xf bound_ctrl:1
	ds_read_b128 v[206:209], v96 offset:26864
	v_add_f32_dpp v58, v58, v58 row_ror:2 row_mask:0xf bank_mask:0xf bound_ctrl:1
	v_fma_f32 v61, v54, v57, v60
	ds_read_b128 v[202:205], v96 offset:26608
	v_add_f32_dpp v58, v58, v58 row_ror:1 row_mask:0xf bank_mask:0xf bound_ctrl:1
	v_pk_fma_f32 v[52:53], v[58:59], v[40:41], v[64:65] op_sel_hi:[0,1,1]
	v_pk_fma_f32 v[48:49], v[58:59], v[42:43], v[66:67] op_sel_hi:[0,1,1]
	v_fma_f32 v61, v58, v56, v61
	ds_read_b32 v210, v97 offset:27120
	ds_read_b64 v[220:221], v98 offset:27184
	ds_write_b32 v99, v61 offset:8704
	s_waitcnt lgkmcnt(9)
	v_pk_mul_f32 v[58:59], v[52:53], v[170:171] op_sel_hi:[0,1]
	v_pk_mul_f32 v[102:103], v[48:49], v[174:175] op_sel_hi:[0,1]
	ds_read_b128 v[32:35], v96 offset:27456
	v_pk_fma_f32 v[58:59], v[52:53], v[172:173], v[58:59] op_sel:[1,0,0]
	v_pk_fma_f32 v[102:103], v[48:49], v[176:177], v[102:103] op_sel:[1,0,0]
	ds_read_b128 v[36:39], v96 offset:27712
	ds_read_b128 v[28:31], v96 offset:27200
	v_pk_add_f32 v[58:59], v[58:59], v[102:103]
	v_pk_mul_f32 v[64:65], v[186:187], v[182:183] op_sel_hi:[0,1]
	v_pk_mul_f32 v[66:67], v[186:187], v[184:185] op_sel_hi:[0,1]
	v_add_f32_dpp v58, v58, v58 row_ror:8 row_mask:0xf bank_mask:0xf bound_ctrl:1
	v_pk_fma_f32 v[64:65], v[52:53], v[166:167], v[64:65]
	v_pk_fma_f32 v[66:67], v[48:49], v[168:169], v[66:67]
	v_add_f32_dpp v58, v58, v58 row_ror:4 row_mask:0xf bank_mask:0xf bound_ctrl:1
	v_add_f32_dpp v60, v59, v59 row_ror:8 row_mask:0xf bank_mask:0xf bound_ctrl:1
	ds_read_b128 v[44:47], v96 offset:28224
	v_add_f32_dpp v58, v58, v58 row_ror:2 row_mask:0xf bank_mask:0xf bound_ctrl:1
	v_fma_f32 v61, v186, v189, v60
	ds_read_b128 v[40:43], v96 offset:27968
	v_add_f32_dpp v58, v58, v58 row_ror:1 row_mask:0xf bank_mask:0xf bound_ctrl:1
	v_pk_fma_f32 v[52:53], v[58:59], v[178:179], v[64:65] op_sel_hi:[0,1,1]
	v_pk_fma_f32 v[48:49], v[58:59], v[180:181], v[66:67] op_sel_hi:[0,1,1]
	v_fma_f32 v61, v58, v188, v61
	ds_read_b32 v54, v97 offset:28480
	ds_read_b64 v[56:57], v98 offset:28544
	ds_write_b32 v99, v61 offset:9216
	s_waitcnt lgkmcnt(9)
	v_pk_mul_f32 v[58:59], v[52:53], v[194:195] op_sel_hi:[0,1]
	v_pk_mul_f32 v[102:103], v[48:49], v[198:199] op_sel_hi:[0,1]
	ds_read_b128 v[170:173], v96 offset:28816
	v_pk_fma_f32 v[58:59], v[52:53], v[196:197], v[58:59] op_sel:[1,0,0]
	v_pk_fma_f32 v[102:103], v[48:49], v[200:201], v[102:103] op_sel:[1,0,0]
	ds_read_b128 v[174:177], v96 offset:29072
	ds_read_b128 v[166:169], v96 offset:28560
	v_pk_add_f32 v[58:59], v[58:59], v[102:103]
	v_pk_mul_f32 v[64:65], v[210:211], v[206:207] op_sel_hi:[0,1]
	v_pk_mul_f32 v[66:67], v[210:211], v[208:209] op_sel_hi:[0,1]
	v_add_f32_dpp v58, v58, v58 row_ror:8 row_mask:0xf bank_mask:0xf bound_ctrl:1
	v_pk_fma_f32 v[64:65], v[52:53], v[190:191], v[64:65]
	v_pk_fma_f32 v[66:67], v[48:49], v[192:193], v[66:67]
	v_add_f32_dpp v58, v58, v58 row_ror:4 row_mask:0xf bank_mask:0xf bound_ctrl:1
	v_add_f32_dpp v60, v59, v59 row_ror:8 row_mask:0xf bank_mask:0xf bound_ctrl:1
	ds_read_b128 v[182:185], v96 offset:29584
	v_add_f32_dpp v58, v58, v58 row_ror:2 row_mask:0xf bank_mask:0xf bound_ctrl:1
	v_fma_f32 v61, v210, v221, v60
	ds_read_b128 v[178:181], v96 offset:29328
	v_add_f32_dpp v58, v58, v58 row_ror:1 row_mask:0xf bank_mask:0xf bound_ctrl:1
	v_pk_fma_f32 v[52:53], v[58:59], v[202:203], v[64:65] op_sel_hi:[0,1,1]
	v_pk_fma_f32 v[48:49], v[58:59], v[204:205], v[66:67] op_sel_hi:[0,1,1]
	v_fma_f32 v61, v58, v220, v61
	ds_read_b32 v186, v97 offset:29840
	ds_read_b64 v[188:189], v98 offset:29904
	ds_write_b32 v99, v61 offset:9728
	s_waitcnt lgkmcnt(9)
	v_pk_mul_f32 v[58:59], v[52:53], v[32:33] op_sel_hi:[0,1]
	v_pk_mul_f32 v[102:103], v[48:49], v[36:37] op_sel_hi:[0,1]
	ds_read_b128 v[194:197], v96 offset:30176
	v_pk_fma_f32 v[58:59], v[52:53], v[34:35], v[58:59] op_sel:[1,0,0]
	v_pk_fma_f32 v[102:103], v[48:49], v[38:39], v[102:103] op_sel:[1,0,0]
	ds_read_b128 v[198:201], v96 offset:30432
	ds_read_b128 v[190:193], v96 offset:29920
	v_pk_add_f32 v[58:59], v[58:59], v[102:103]
	v_pk_mul_f32 v[64:65], v[54:55], v[44:45] op_sel_hi:[0,1]
	v_pk_mul_f32 v[66:67], v[54:55], v[46:47] op_sel_hi:[0,1]
	v_add_f32_dpp v58, v58, v58 row_ror:8 row_mask:0xf bank_mask:0xf bound_ctrl:1
	v_pk_fma_f32 v[64:65], v[52:53], v[28:29], v[64:65]
	v_pk_fma_f32 v[66:67], v[48:49], v[30:31], v[66:67]
	v_add_f32_dpp v58, v58, v58 row_ror:4 row_mask:0xf bank_mask:0xf bound_ctrl:1
	v_add_f32_dpp v60, v59, v59 row_ror:8 row_mask:0xf bank_mask:0xf bound_ctrl:1
	ds_read_b128 v[206:209], v96 offset:30944
	v_add_f32_dpp v58, v58, v58 row_ror:2 row_mask:0xf bank_mask:0xf bound_ctrl:1
	v_fma_f32 v61, v54, v57, v60
	ds_read_b128 v[202:205], v96 offset:30688
	v_add_f32_dpp v58, v58, v58 row_ror:1 row_mask:0xf bank_mask:0xf bound_ctrl:1
	v_pk_fma_f32 v[52:53], v[58:59], v[40:41], v[64:65] op_sel_hi:[0,1,1]
	v_pk_fma_f32 v[48:49], v[58:59], v[42:43], v[66:67] op_sel_hi:[0,1,1]
	v_fma_f32 v61, v58, v56, v61
	ds_read_b32 v210, v97 offset:31200
	ds_read_b64 v[220:221], v98 offset:31264
	ds_write_b32 v99, v61 offset:10240
	s_waitcnt lgkmcnt(9)
	v_pk_mul_f32 v[58:59], v[52:53], v[170:171] op_sel_hi:[0,1]
	v_pk_mul_f32 v[102:103], v[48:49], v[174:175] op_sel_hi:[0,1]
	ds_read_b128 v[32:35], v96 offset:31536
	v_pk_fma_f32 v[58:59], v[52:53], v[172:173], v[58:59] op_sel:[1,0,0]
	v_pk_fma_f32 v[102:103], v[48:49], v[176:177], v[102:103] op_sel:[1,0,0]
	ds_read_b128 v[36:39], v96 offset:31792
	ds_read_b128 v[28:31], v96 offset:31280
	v_pk_add_f32 v[58:59], v[58:59], v[102:103]
	v_pk_mul_f32 v[64:65], v[186:187], v[182:183] op_sel_hi:[0,1]
	v_pk_mul_f32 v[66:67], v[186:187], v[184:185] op_sel_hi:[0,1]
	v_add_f32_dpp v58, v58, v58 row_ror:8 row_mask:0xf bank_mask:0xf bound_ctrl:1
	v_pk_fma_f32 v[64:65], v[52:53], v[166:167], v[64:65]
	v_pk_fma_f32 v[66:67], v[48:49], v[168:169], v[66:67]
	v_add_f32_dpp v58, v58, v58 row_ror:4 row_mask:0xf bank_mask:0xf bound_ctrl:1
	v_add_f32_dpp v60, v59, v59 row_ror:8 row_mask:0xf bank_mask:0xf bound_ctrl:1
	ds_read_b128 v[44:47], v96 offset:32304
	v_add_f32_dpp v58, v58, v58 row_ror:2 row_mask:0xf bank_mask:0xf bound_ctrl:1
	v_fma_f32 v61, v186, v189, v60
	ds_read_b128 v[40:43], v96 offset:32048
	v_add_f32_dpp v58, v58, v58 row_ror:1 row_mask:0xf bank_mask:0xf bound_ctrl:1
	v_pk_fma_f32 v[52:53], v[58:59], v[178:179], v[64:65] op_sel_hi:[0,1,1]
	v_pk_fma_f32 v[48:49], v[58:59], v[180:181], v[66:67] op_sel_hi:[0,1,1]
	v_fma_f32 v61, v58, v188, v61
	ds_read_b32 v54, v97 offset:32560
	ds_read_b64 v[56:57], v98 offset:32624
	ds_write_b32 v99, v61 offset:10752
	s_waitcnt lgkmcnt(9)
	v_pk_mul_f32 v[58:59], v[52:53], v[194:195] op_sel_hi:[0,1]
	v_pk_mul_f32 v[102:103], v[48:49], v[198:199] op_sel_hi:[0,1]
	ds_read_b128 v[170:173], v96 offset:32896
	v_pk_fma_f32 v[58:59], v[52:53], v[196:197], v[58:59] op_sel:[1,0,0]
	v_pk_fma_f32 v[102:103], v[48:49], v[200:201], v[102:103] op_sel:[1,0,0]
	ds_read_b128 v[174:177], v96 offset:33152
	ds_read_b128 v[166:169], v96 offset:32640
	v_pk_add_f32 v[58:59], v[58:59], v[102:103]
	v_pk_mul_f32 v[64:65], v[210:211], v[206:207] op_sel_hi:[0,1]
	v_pk_mul_f32 v[66:67], v[210:211], v[208:209] op_sel_hi:[0,1]
	v_add_f32_dpp v58, v58, v58 row_ror:8 row_mask:0xf bank_mask:0xf bound_ctrl:1
	v_pk_fma_f32 v[64:65], v[52:53], v[190:191], v[64:65]
	v_pk_fma_f32 v[66:67], v[48:49], v[192:193], v[66:67]
	v_add_f32_dpp v58, v58, v58 row_ror:4 row_mask:0xf bank_mask:0xf bound_ctrl:1
	v_add_f32_dpp v60, v59, v59 row_ror:8 row_mask:0xf bank_mask:0xf bound_ctrl:1
	ds_read_b128 v[182:185], v96 offset:33664
	v_add_f32_dpp v58, v58, v58 row_ror:2 row_mask:0xf bank_mask:0xf bound_ctrl:1
	v_fma_f32 v61, v210, v221, v60
	ds_read_b128 v[178:181], v96 offset:33408
	v_add_f32_dpp v58, v58, v58 row_ror:1 row_mask:0xf bank_mask:0xf bound_ctrl:1
	v_pk_fma_f32 v[52:53], v[58:59], v[202:203], v[64:65] op_sel_hi:[0,1,1]
	v_pk_fma_f32 v[48:49], v[58:59], v[204:205], v[66:67] op_sel_hi:[0,1,1]
	v_fma_f32 v61, v58, v220, v61
	ds_read_b32 v186, v97 offset:33920
	ds_read_b64 v[188:189], v98 offset:33984
	ds_write_b32 v99, v61 offset:11264
	s_waitcnt lgkmcnt(9)
	v_pk_mul_f32 v[58:59], v[52:53], v[32:33] op_sel_hi:[0,1]
	v_pk_mul_f32 v[102:103], v[48:49], v[36:37] op_sel_hi:[0,1]
	ds_read_b128 v[194:197], v96 offset:34256
	v_pk_fma_f32 v[58:59], v[52:53], v[34:35], v[58:59] op_sel:[1,0,0]
	v_pk_fma_f32 v[102:103], v[48:49], v[38:39], v[102:103] op_sel:[1,0,0]
	ds_read_b128 v[198:201], v96 offset:34512
	ds_read_b128 v[190:193], v96 offset:34000
	v_pk_add_f32 v[58:59], v[58:59], v[102:103]
	v_pk_mul_f32 v[64:65], v[54:55], v[44:45] op_sel_hi:[0,1]
	v_pk_mul_f32 v[66:67], v[54:55], v[46:47] op_sel_hi:[0,1]
	v_add_f32_dpp v58, v58, v58 row_ror:8 row_mask:0xf bank_mask:0xf bound_ctrl:1
	v_pk_fma_f32 v[64:65], v[52:53], v[28:29], v[64:65]
	v_pk_fma_f32 v[66:67], v[48:49], v[30:31], v[66:67]
	v_add_f32_dpp v58, v58, v58 row_ror:4 row_mask:0xf bank_mask:0xf bound_ctrl:1
	v_add_f32_dpp v60, v59, v59 row_ror:8 row_mask:0xf bank_mask:0xf bound_ctrl:1
	ds_read_b128 v[206:209], v96 offset:35024
	v_add_f32_dpp v58, v58, v58 row_ror:2 row_mask:0xf bank_mask:0xf bound_ctrl:1
	v_fma_f32 v61, v54, v57, v60
	ds_read_b128 v[202:205], v96 offset:34768
	v_add_f32_dpp v58, v58, v58 row_ror:1 row_mask:0xf bank_mask:0xf bound_ctrl:1
	v_pk_fma_f32 v[52:53], v[58:59], v[40:41], v[64:65] op_sel_hi:[0,1,1]
	v_pk_fma_f32 v[48:49], v[58:59], v[42:43], v[66:67] op_sel_hi:[0,1,1]
	v_fma_f32 v61, v58, v56, v61
	ds_read_b32 v210, v97 offset:35280
	ds_read_b64 v[220:221], v98 offset:35344
	ds_write_b32 v99, v61 offset:11776
	s_waitcnt lgkmcnt(9)
	v_pk_mul_f32 v[58:59], v[52:53], v[170:171] op_sel_hi:[0,1]
	v_pk_mul_f32 v[102:103], v[48:49], v[174:175] op_sel_hi:[0,1]
	ds_read_b128 v[32:35], v96 offset:35616
	v_pk_fma_f32 v[58:59], v[52:53], v[172:173], v[58:59] op_sel:[1,0,0]
	v_pk_fma_f32 v[102:103], v[48:49], v[176:177], v[102:103] op_sel:[1,0,0]
	ds_read_b128 v[36:39], v96 offset:35872
	ds_read_b128 v[28:31], v96 offset:35360
	v_pk_add_f32 v[58:59], v[58:59], v[102:103]
	v_pk_mul_f32 v[64:65], v[186:187], v[182:183] op_sel_hi:[0,1]
	v_pk_mul_f32 v[66:67], v[186:187], v[184:185] op_sel_hi:[0,1]
	v_add_f32_dpp v58, v58, v58 row_ror:8 row_mask:0xf bank_mask:0xf bound_ctrl:1
	v_pk_fma_f32 v[64:65], v[52:53], v[166:167], v[64:65]
	v_pk_fma_f32 v[66:67], v[48:49], v[168:169], v[66:67]
	v_add_f32_dpp v58, v58, v58 row_ror:4 row_mask:0xf bank_mask:0xf bound_ctrl:1
	v_add_f32_dpp v60, v59, v59 row_ror:8 row_mask:0xf bank_mask:0xf bound_ctrl:1
	ds_read_b128 v[44:47], v96 offset:36384
	v_add_f32_dpp v58, v58, v58 row_ror:2 row_mask:0xf bank_mask:0xf bound_ctrl:1
	v_fma_f32 v61, v186, v189, v60
	ds_read_b128 v[40:43], v96 offset:36128
	v_add_f32_dpp v58, v58, v58 row_ror:1 row_mask:0xf bank_mask:0xf bound_ctrl:1
	v_pk_fma_f32 v[52:53], v[58:59], v[178:179], v[64:65] op_sel_hi:[0,1,1]
	v_pk_fma_f32 v[48:49], v[58:59], v[180:181], v[66:67] op_sel_hi:[0,1,1]
	v_fma_f32 v61, v58, v188, v61
	ds_read_b32 v54, v97 offset:36640
	ds_read_b64 v[56:57], v98 offset:36704
	ds_write_b32 v99, v61 offset:12288
	s_waitcnt lgkmcnt(9)
	v_pk_mul_f32 v[58:59], v[52:53], v[194:195] op_sel_hi:[0,1]
	v_pk_mul_f32 v[102:103], v[48:49], v[198:199] op_sel_hi:[0,1]
	ds_read_b128 v[170:173], v96 offset:36976
	v_pk_fma_f32 v[58:59], v[52:53], v[196:197], v[58:59] op_sel:[1,0,0]
	v_pk_fma_f32 v[102:103], v[48:49], v[200:201], v[102:103] op_sel:[1,0,0]
	ds_read_b128 v[174:177], v96 offset:37232
	ds_read_b128 v[166:169], v96 offset:36720
	v_pk_add_f32 v[58:59], v[58:59], v[102:103]
	v_pk_mul_f32 v[64:65], v[210:211], v[206:207] op_sel_hi:[0,1]
	v_pk_mul_f32 v[66:67], v[210:211], v[208:209] op_sel_hi:[0,1]
	v_add_f32_dpp v58, v58, v58 row_ror:8 row_mask:0xf bank_mask:0xf bound_ctrl:1
	v_pk_fma_f32 v[64:65], v[52:53], v[190:191], v[64:65]
	v_pk_fma_f32 v[66:67], v[48:49], v[192:193], v[66:67]
	v_add_f32_dpp v58, v58, v58 row_ror:4 row_mask:0xf bank_mask:0xf bound_ctrl:1
	v_add_f32_dpp v60, v59, v59 row_ror:8 row_mask:0xf bank_mask:0xf bound_ctrl:1
	ds_read_b128 v[182:185], v96 offset:37744
	v_add_f32_dpp v58, v58, v58 row_ror:2 row_mask:0xf bank_mask:0xf bound_ctrl:1
	v_fma_f32 v61, v210, v221, v60
	ds_read_b128 v[178:181], v96 offset:37488
	v_add_f32_dpp v58, v58, v58 row_ror:1 row_mask:0xf bank_mask:0xf bound_ctrl:1
	v_pk_fma_f32 v[52:53], v[58:59], v[202:203], v[64:65] op_sel_hi:[0,1,1]
	v_pk_fma_f32 v[48:49], v[58:59], v[204:205], v[66:67] op_sel_hi:[0,1,1]
	v_fma_f32 v61, v58, v220, v61
	ds_read_b32 v186, v97 offset:38000
	ds_read_b64 v[188:189], v98 offset:38064
	ds_write_b32 v99, v61 offset:12800
	s_waitcnt lgkmcnt(9)
	v_pk_mul_f32 v[58:59], v[52:53], v[32:33] op_sel_hi:[0,1]
	v_pk_mul_f32 v[102:103], v[48:49], v[36:37] op_sel_hi:[0,1]
	ds_read_b128 v[194:197], v96 offset:38336
	v_pk_fma_f32 v[58:59], v[52:53], v[34:35], v[58:59] op_sel:[1,0,0]
	v_pk_fma_f32 v[102:103], v[48:49], v[38:39], v[102:103] op_sel:[1,0,0]
	ds_read_b128 v[198:201], v96 offset:38592
	ds_read_b128 v[190:193], v96 offset:38080
	v_pk_add_f32 v[58:59], v[58:59], v[102:103]
	v_pk_mul_f32 v[64:65], v[54:55], v[44:45] op_sel_hi:[0,1]
	v_pk_mul_f32 v[66:67], v[54:55], v[46:47] op_sel_hi:[0,1]
	v_add_f32_dpp v58, v58, v58 row_ror:8 row_mask:0xf bank_mask:0xf bound_ctrl:1
	v_pk_fma_f32 v[64:65], v[52:53], v[28:29], v[64:65]
	v_pk_fma_f32 v[66:67], v[48:49], v[30:31], v[66:67]
	v_add_f32_dpp v58, v58, v58 row_ror:4 row_mask:0xf bank_mask:0xf bound_ctrl:1
	v_add_f32_dpp v60, v59, v59 row_ror:8 row_mask:0xf bank_mask:0xf bound_ctrl:1
	ds_read_b128 v[206:209], v96 offset:39104
	v_add_f32_dpp v58, v58, v58 row_ror:2 row_mask:0xf bank_mask:0xf bound_ctrl:1
	v_fma_f32 v61, v54, v57, v60
	ds_read_b128 v[202:205], v96 offset:38848
	v_add_f32_dpp v58, v58, v58 row_ror:1 row_mask:0xf bank_mask:0xf bound_ctrl:1
	v_pk_fma_f32 v[52:53], v[58:59], v[40:41], v[64:65] op_sel_hi:[0,1,1]
	v_pk_fma_f32 v[48:49], v[58:59], v[42:43], v[66:67] op_sel_hi:[0,1,1]
	v_fma_f32 v61, v58, v56, v61
	ds_read_b32 v210, v97 offset:39360
	ds_read_b64 v[220:221], v98 offset:39424
	ds_write_b32 v99, v61 offset:13312
	s_waitcnt lgkmcnt(9)
	v_pk_mul_f32 v[58:59], v[52:53], v[170:171] op_sel_hi:[0,1]
	v_pk_mul_f32 v[102:103], v[48:49], v[174:175] op_sel_hi:[0,1]
	ds_read_b128 v[32:35], v96 offset:39696
	v_pk_fma_f32 v[58:59], v[52:53], v[172:173], v[58:59] op_sel:[1,0,0]
	v_pk_fma_f32 v[102:103], v[48:49], v[176:177], v[102:103] op_sel:[1,0,0]
	ds_read_b128 v[36:39], v96 offset:39952
	ds_read_b128 v[28:31], v96 offset:39440
	v_pk_add_f32 v[58:59], v[58:59], v[102:103]
	v_pk_mul_f32 v[64:65], v[186:187], v[182:183] op_sel_hi:[0,1]
	v_pk_mul_f32 v[66:67], v[186:187], v[184:185] op_sel_hi:[0,1]
	v_add_f32_dpp v58, v58, v58 row_ror:8 row_mask:0xf bank_mask:0xf bound_ctrl:1
	v_pk_fma_f32 v[64:65], v[52:53], v[166:167], v[64:65]
	v_pk_fma_f32 v[66:67], v[48:49], v[168:169], v[66:67]
	v_add_f32_dpp v58, v58, v58 row_ror:4 row_mask:0xf bank_mask:0xf bound_ctrl:1
	v_add_f32_dpp v60, v59, v59 row_ror:8 row_mask:0xf bank_mask:0xf bound_ctrl:1
	ds_read_b128 v[44:47], v96 offset:40464
	v_add_f32_dpp v58, v58, v58 row_ror:2 row_mask:0xf bank_mask:0xf bound_ctrl:1
	v_fma_f32 v61, v186, v189, v60
	ds_read_b128 v[40:43], v96 offset:40208
	v_add_f32_dpp v58, v58, v58 row_ror:1 row_mask:0xf bank_mask:0xf bound_ctrl:1
	v_pk_fma_f32 v[52:53], v[58:59], v[178:179], v[64:65] op_sel_hi:[0,1,1]
	v_pk_fma_f32 v[48:49], v[58:59], v[180:181], v[66:67] op_sel_hi:[0,1,1]
	v_fma_f32 v61, v58, v188, v61
	ds_read_b32 v54, v97 offset:40720
	ds_read_b64 v[56:57], v98 offset:40784
	ds_write_b32 v99, v61 offset:13824
	s_waitcnt lgkmcnt(9)
	v_pk_mul_f32 v[58:59], v[52:53], v[194:195] op_sel_hi:[0,1]
	v_pk_mul_f32 v[102:103], v[48:49], v[198:199] op_sel_hi:[0,1]
	ds_read_b128 v[170:173], v96 offset:41056
	v_pk_fma_f32 v[58:59], v[52:53], v[196:197], v[58:59] op_sel:[1,0,0]
	v_pk_fma_f32 v[102:103], v[48:49], v[200:201], v[102:103] op_sel:[1,0,0]
	ds_read_b128 v[174:177], v96 offset:41312
	ds_read_b128 v[166:169], v96 offset:40800
	v_pk_add_f32 v[58:59], v[58:59], v[102:103]
	v_pk_mul_f32 v[64:65], v[210:211], v[206:207] op_sel_hi:[0,1]
	v_pk_mul_f32 v[66:67], v[210:211], v[208:209] op_sel_hi:[0,1]
	v_add_f32_dpp v58, v58, v58 row_ror:8 row_mask:0xf bank_mask:0xf bound_ctrl:1
	v_pk_fma_f32 v[64:65], v[52:53], v[190:191], v[64:65]
	v_pk_fma_f32 v[66:67], v[48:49], v[192:193], v[66:67]
	v_add_f32_dpp v58, v58, v58 row_ror:4 row_mask:0xf bank_mask:0xf bound_ctrl:1
	v_add_f32_dpp v60, v59, v59 row_ror:8 row_mask:0xf bank_mask:0xf bound_ctrl:1
	ds_read_b128 v[182:185], v96 offset:41824
	v_add_f32_dpp v58, v58, v58 row_ror:2 row_mask:0xf bank_mask:0xf bound_ctrl:1
	v_fma_f32 v61, v210, v221, v60
	ds_read_b128 v[178:181], v96 offset:41568
	v_add_f32_dpp v58, v58, v58 row_ror:1 row_mask:0xf bank_mask:0xf bound_ctrl:1
	v_pk_fma_f32 v[52:53], v[58:59], v[202:203], v[64:65] op_sel_hi:[0,1,1]
	v_pk_fma_f32 v[48:49], v[58:59], v[204:205], v[66:67] op_sel_hi:[0,1,1]
	v_fma_f32 v61, v58, v220, v61
	ds_read_b32 v186, v97 offset:42080
	ds_read_b64 v[188:189], v98 offset:42144
	ds_write_b32 v99, v61 offset:14336
	s_waitcnt lgkmcnt(9)
	v_pk_mul_f32 v[58:59], v[52:53], v[32:33] op_sel_hi:[0,1]
	v_pk_mul_f32 v[102:103], v[48:49], v[36:37] op_sel_hi:[0,1]
	ds_read_b128 v[194:197], v96 offset:42416
	v_pk_fma_f32 v[58:59], v[52:53], v[34:35], v[58:59] op_sel:[1,0,0]
	v_pk_fma_f32 v[102:103], v[48:49], v[38:39], v[102:103] op_sel:[1,0,0]
	ds_read_b128 v[198:201], v96 offset:42672
	ds_read_b128 v[190:193], v96 offset:42160
	v_pk_add_f32 v[58:59], v[58:59], v[102:103]
	v_pk_mul_f32 v[64:65], v[54:55], v[44:45] op_sel_hi:[0,1]
	v_pk_mul_f32 v[66:67], v[54:55], v[46:47] op_sel_hi:[0,1]
	v_add_f32_dpp v58, v58, v58 row_ror:8 row_mask:0xf bank_mask:0xf bound_ctrl:1
	v_pk_fma_f32 v[64:65], v[52:53], v[28:29], v[64:65]
	v_pk_fma_f32 v[66:67], v[48:49], v[30:31], v[66:67]
	v_add_f32_dpp v58, v58, v58 row_ror:4 row_mask:0xf bank_mask:0xf bound_ctrl:1
	v_add_f32_dpp v60, v59, v59 row_ror:8 row_mask:0xf bank_mask:0xf bound_ctrl:1
	ds_read_b128 v[206:209], v96 offset:43184
	v_add_f32_dpp v58, v58, v58 row_ror:2 row_mask:0xf bank_mask:0xf bound_ctrl:1
	v_fma_f32 v61, v54, v57, v60
	ds_read_b128 v[202:205], v96 offset:42928
	v_add_f32_dpp v58, v58, v58 row_ror:1 row_mask:0xf bank_mask:0xf bound_ctrl:1
	v_pk_fma_f32 v[52:53], v[58:59], v[40:41], v[64:65] op_sel_hi:[0,1,1]
	v_pk_fma_f32 v[48:49], v[58:59], v[42:43], v[66:67] op_sel_hi:[0,1,1]
	v_fma_f32 v61, v58, v56, v61
	ds_read_b32 v210, v97 offset:43440
	ds_read_b64 v[220:221], v98 offset:43504
	ds_write_b32 v99, v61 offset:14848
	s_waitcnt lgkmcnt(9)
	v_pk_mul_f32 v[58:59], v[52:53], v[170:171] op_sel_hi:[0,1]
	v_pk_mul_f32 v[102:103], v[48:49], v[174:175] op_sel_hi:[0,1]
	v_pk_fma_f32 v[58:59], v[52:53], v[172:173], v[58:59] op_sel:[1,0,0]
	v_pk_fma_f32 v[102:103], v[48:49], v[176:177], v[102:103] op_sel:[1,0,0]
	v_pk_add_f32 v[58:59], v[58:59], v[102:103]
	v_pk_mul_f32 v[64:65], v[186:187], v[182:183] op_sel_hi:[0,1]
	v_pk_mul_f32 v[66:67], v[186:187], v[184:185] op_sel_hi:[0,1]
	v_add_f32_dpp v58, v58, v58 row_ror:8 row_mask:0xf bank_mask:0xf bound_ctrl:1
	v_pk_fma_f32 v[64:65], v[52:53], v[166:167], v[64:65]
	v_pk_fma_f32 v[66:67], v[48:49], v[168:169], v[66:67]
	v_add_f32_dpp v58, v58, v58 row_ror:4 row_mask:0xf bank_mask:0xf bound_ctrl:1
	v_add_f32_dpp v60, v59, v59 row_ror:8 row_mask:0xf bank_mask:0xf bound_ctrl:1
	s_nop 0
	v_add_f32_dpp v58, v58, v58 row_ror:2 row_mask:0xf bank_mask:0xf bound_ctrl:1
	v_fma_f32 v61, v186, v189, v60
	s_nop 0
	v_add_f32_dpp v58, v58, v58 row_ror:1 row_mask:0xf bank_mask:0xf bound_ctrl:1
	v_pk_fma_f32 v[52:53], v[58:59], v[178:179], v[64:65] op_sel_hi:[0,1,1]
	v_pk_fma_f32 v[48:49], v[58:59], v[180:181], v[66:67] op_sel_hi:[0,1,1]
	v_fma_f32 v61, v58, v188, v61
	ds_write_b32 v99, v61 offset:15360
	s_waitcnt lgkmcnt(2)
	v_pk_mul_f32 v[58:59], v[52:53], v[194:195] op_sel_hi:[0,1]
	v_pk_mul_f32 v[102:103], v[48:49], v[198:199] op_sel_hi:[0,1]
	v_pk_fma_f32 v[58:59], v[52:53], v[196:197], v[58:59] op_sel:[1,0,0]
	v_pk_fma_f32 v[102:103], v[48:49], v[200:201], v[102:103] op_sel:[1,0,0]
	v_pk_add_f32 v[58:59], v[58:59], v[102:103]
	v_pk_mul_f32 v[64:65], v[210:211], v[206:207] op_sel_hi:[0,1]
	v_pk_mul_f32 v[66:67], v[210:211], v[208:209] op_sel_hi:[0,1]
	v_add_f32_dpp v58, v58, v58 row_ror:8 row_mask:0xf bank_mask:0xf bound_ctrl:1
	v_pk_fma_f32 v[64:65], v[52:53], v[190:191], v[64:65]
	v_pk_fma_f32 v[66:67], v[48:49], v[192:193], v[66:67]
	v_add_f32_dpp v58, v58, v58 row_ror:4 row_mask:0xf bank_mask:0xf bound_ctrl:1
	v_add_f32_dpp v60, v59, v59 row_ror:8 row_mask:0xf bank_mask:0xf bound_ctrl:1
	s_nop 0
	v_add_f32_dpp v58, v58, v58 row_ror:2 row_mask:0xf bank_mask:0xf bound_ctrl:1
	v_fma_f32 v61, v210, v221, v60
	s_nop 0
	v_add_f32_dpp v58, v58, v58 row_ror:1 row_mask:0xf bank_mask:0xf bound_ctrl:1
	v_pk_fma_f32 v[52:53], v[58:59], v[202:203], v[64:65] op_sel_hi:[0,1,1]
	v_pk_fma_f32 v[48:49], v[58:59], v[204:205], v[66:67] op_sel_hi:[0,1,1]
	v_fma_f32 v61, v58, v220, v61
	ds_write_b32 v99, v61 offset:15872
	s_setprio 0
	s_mov_b64 s[78:79], 0
